# grid barrier: the per-CU acquire invalidate is issued by wave 0 just before the barrier's opening store-drain wait, so it overlaps the store acknowledgements instead of sitting in front of the arrival
# baseline (speedup 1.0000x reference)
.LBB0_29:
	v_readfirstlane_b32 s98, v196
	s_cmp_lg_u32 s98, 0
	s_cbranch_scc1 .Lei_0
	buffer_inv sc1

.LBB0_1060:
	s_cmp_gt_i32 s95, 10
	s_cselect_b64 s[0:1], -1, 0
	s_and_b64 s[2:3], s[10:11], s[0:1]
	v_readlane_b32 s42, v250, 61
	s_andn2_b64 vcc, exec, s[2:3]
	v_readlane_b32 s43, v250, 62
	s_cbranch_vccnz .LBB0_1112
	v_readfirstlane_b32 s98, v196
	s_cmp_lg_u32 s98, 0
	s_cbranch_scc1 .Lei_7
	buffer_inv sc1
.Lei_7:
	s_waitcnt vmcnt(0)
	s_barrier
	s_mov_b64 s[4:5], exec
	v_readlane_b32 s2, v250, 4
	v_readlane_b32 s3, v250, 5
	s_and_b64 s[2:3], s[4:5], s[2:3]
	s_mov_b64 exec, s[2:3]
	s_cbranch_execz .LBB0_1111
	s_add_i32 s2, 0, 0x22fc0
	v_mov_b32_e32 v0, s2
	s_waitcnt vmcnt(0) expcnt(0) lgkmcnt(0)
	ds_read_b32 v2, v0
	s_add_i32 s2, 0, 0x22fc4
	v_mov_b32_e32 v0, s2
	ds_read_b32 v0, v0
	s_waitcnt lgkmcnt(1)
	v_cmp_ne_u32_e32 vcc, 0, v2
	s_cbranch_vccnz .LBB0_1077
	s_add_u32 s10, s68, 0x14200
	s_addc_u32 s11, s69, 0
	s_add_u32 s16, s68, 0x14400
	s_addc_u32 s17, s69, 0
	s_add_u32 s18, s68, 0x14500
	s_addc_u32 s19, s69, 0
	s_add_u32 s20, s68, 0x14600
	s_addc_u32 s21, s69, 0
	s_add_u32 s22, s68, 0x14700
	s_addc_u32 s23, s69, 0
	s_add_u32 s24, s68, 0x14800
	s_addc_u32 s25, s69, 0
	s_add_u32 s26, s68, 0x14900
	s_addc_u32 s27, s69, 0
	s_add_u32 s28, s68, 0x14a00
	s_addc_u32 s29, s69, 0
	s_add_u32 s36, s68, 0x14b00
	s_addc_u32 s37, s69, 0
	s_add_u32 s40, s68, 0x14c00
	s_addc_u32 s41, s69, 0
	s_add_u32 s44, s68, 0x14d00
	s_addc_u32 s45, s69, 0
	s_add_u32 s46, s68, 0x14e00
	s_addc_u32 s47, s69, 0
	s_add_u32 s48, s68, 0x14f00
	s_addc_u32 s49, s69, 0
	s_add_u32 s50, s68, 0x15000
	s_addc_u32 s51, s69, 0
	s_add_u32 s52, s68, 0x15100
	s_addc_u32 s53, s69, 0
	s_add_u32 s54, s68, 0x15200
	v_readlane_b32 s2, v250, 0
	s_addc_u32 s55, s69, 0
	s_mul_i32 s2, s39, s2
	s_add_u32 s12, s68, 0x15300
	s_mul_i32 s2, s2, s38
	s_addc_u32 s13, s69, 0
	s_mov_b32 s3, 1
	v_mov_b32_e32 v16, 0
	s_branch .LBB0_1065

.LBB0_1129:
	s_cmp_gt_i32 s95, 11
	s_cselect_b64 s[0:1], -1, 0
	s_and_b64 s[2:3], s[4:5], s[0:1]
	s_andn2_b64 vcc, exec, s[2:3]
	s_cbranch_vccnz .LBB0_1181
	v_readfirstlane_b32 s98, v196
	s_cmp_lg_u32 s98, 0
	s_cbranch_scc1 .Lei_8
	buffer_inv sc1
.Lei_8:
	s_waitcnt vmcnt(0)
	s_barrier
	s_mov_b64 s[4:5], exec
	v_readlane_b32 s2, v250, 4
	v_readlane_b32 s3, v250, 5
	s_and_b64 s[2:3], s[4:5], s[2:3]
	s_mov_b64 exec, s[2:3]
	s_cbranch_execz .LBB0_1180
	s_add_i32 s2, 0, 0x22fc0
	v_mov_b32_e32 v0, s2
	s_waitcnt vmcnt(0) expcnt(0) lgkmcnt(0)
	ds_read_b32 v2, v0
	s_add_i32 s2, 0, 0x22fc4
	v_mov_b32_e32 v0, s2
	ds_read_b32 v0, v0
	s_waitcnt lgkmcnt(1)
	v_cmp_ne_u32_e32 vcc, 0, v2
	s_cbranch_vccnz .LBB0_1146
	s_add_u32 s8, s68, 0x14200
	s_addc_u32 s9, s69, 0
	s_add_u32 s10, s68, 0x14400
	s_addc_u32 s11, s69, 0
	s_add_u32 s12, s68, 0x14500
	s_addc_u32 s13, s69, 0
	s_add_u32 s14, s68, 0x14600
	s_addc_u32 s15, s69, 0
	s_add_u32 s16, s68, 0x14700
	s_addc_u32 s17, s69, 0
	s_add_u32 s18, s68, 0x14800
	s_addc_u32 s19, s69, 0
	s_add_u32 s20, s68, 0x14900
	s_addc_u32 s21, s69, 0
	s_add_u32 s22, s68, 0x14a00
	s_addc_u32 s23, s69, 0
	s_add_u32 s24, s68, 0x14b00
	s_addc_u32 s25, s69, 0
	s_add_u32 s26, s68, 0x14c00
	s_addc_u32 s27, s69, 0
	s_add_u32 s28, s68, 0x14d00
	s_addc_u32 s29, s69, 0
	s_add_u32 s36, s68, 0x14e00
	s_addc_u32 s37, s69, 0
	s_add_u32 s40, s68, 0x14f00
	s_addc_u32 s41, s69, 0
	s_add_u32 s42, s68, 0x15000
	s_addc_u32 s43, s69, 0
	s_add_u32 s44, s68, 0x15100
	s_addc_u32 s45, s69, 0
	s_add_u32 s46, s68, 0x15200
	v_readlane_b32 s2, v250, 0
	s_addc_u32 s47, s69, 0
	s_mul_i32 s2, s39, s2
	s_add_u32 s48, s68, 0x15300
	s_mul_i32 s2, s2, s38
	s_addc_u32 s49, s69, 0
	s_mov_b32 s3, 1
	v_mov_b32_e32 v16, 0
	s_branch .LBB0_1134
